# k10 + diff attention ping-pong: waves 4-7 run P.V one tile interval behind waves 0-3 (V triple-buffered) so matrix and softmax phases of the two waves of a SIMD overlap
# baseline (speedup 1.0000x reference)
.LBB0_383:
	s_or_b64 exec, exec, s[6:7]
	s_lshl_b32 s4, s3, 13
	s_add_i32 s9, s4, 0
	s_lshl_b32 s4, s64, 2
	s_add_i32 s60, s4, 0
	s_lshr_b32 s65, s33, 7
	s_lshl_b32 s40, s3, 5
	s_mov_b32 s41, s45
	s_add_i32 s61, s9, 0xc000
	s_add_i32 s63, s60, 0x23100
	s_add_i32 s65, s65, 2
	s_lshl_b64 s[4:5], s[40:41], 12
	s_add_u32 s66, s18, s4
	s_addc_u32 s67, s19, s5
	s_lshl_b32 s4, s33, 12
	s_and_b32 s4, s4, 0x1c0000
	s_add_u32 s68, s16, s4
	s_addc_u32 s69, s17, 0
	v_writelane_b32 v255, s82, 2
	s_add_i32 s70, 0, 0x23080
	v_mov_b32_e32 v190, s70
	v_cndmask_b32_e64 v0, 0, 1, s[82:83]
	v_writelane_b32 v255, s83, 3
	v_cmp_ne_u32_e64 s[10:11], 1, v0
	s_movk_i32 s71, 0x70
	s_mov_b32 s72, 0x3fb8aa3b
	s_mov_b32 s73, 0xc2ce8ed0
	s_mov_b32 s74, 0x42b17218
	s_mov_b32 s8, 0x3f4ccccd
	s_mov_b32 s75, 0xffff0000
	v_mov_b32_e32 v191, 0x3727c5ac
	s_mov_b32 s76, 0xf800000
	v_mov_b32_e32 v192, 0x260
	s_movk_i32 s77, 0x7fff
	s_mov_b32 s78, 0x39302000
	s_mov_b32 s79, 0x13003000
	s_mov_b32 s80, 0x39303000
	s_movk_i32 s81, 0x6000
	v_mov_b32_e32 v193, 0xff800000
	v_mov_b32_e32 v194, 0x7f800000
	s_mov_b32 s82, 0
	s_mov_b32 s83, 0
	s_waitcnt lgkmcnt(0)
	s_barrier
	s_branch .LBB0_385

.LBB0_396:
	s_or_b32 s4, s4, s90
	s_mul_i32 s4, s4, 0x102000
	s_add_i32 s44, s91, s4
	s_xor_b64 s[50:51], s[52:53], -1
	v_mbcnt_lo_u32_b32 v32, -1, 0
	v_mbcnt_hi_u32_b32 v32, -1, v32
	s_lshl_b32 s100, s3, 10
	s_lshr_b32 s101, s33, 8
	v_lshrrev_b32_e32 v236, 4, v32
	s_lshl_b32 s97, s3, 2
	v_add_u32_e32 v236, s97, v236
	v_and_b32_e32 v237, 15, v32
	v_and_b32_e32 v238, 7, v236
	v_xor_b32_e32 v237, v237, v238
	v_lshlrev_b32_e32 v232, 8, v236
	v_lshl_or_b32 v232, v237, 4, v232
	v_add_u32_e32 v233, 0x2000, v232
	s_lshr_b32 s98, s3, 1
	s_lshl_b32 s98, s98, 3
	v_bfe_u32 v236, v32, 2, 3
	v_add_u32_e32 v236, s98, v236
	s_and_b32 s99, s3, 1
	s_lshl_b32 s99, s99, 1
	v_lshrrev_b32_e32 v237, 5, v32
	v_add_u32_e32 v237, s99, v237
	v_and_b32_e32 v238, 3, v32
	v_lshlrev_b32_e32 v238, 4, v238
	v_lshl_or_b32 v238, v237, 6, v238
	v_lshl_or_b32 v234, v236, 8, v238
	v_add_u32_e32 v235, 0x2000, v234
	s_lshl_b64 s[54:55], s[44:45], 1
	v_and_b32_e32 v198, 31, v32
	s_add_u32 s54, s26, s54
	v_or_b32_e32 v184, s40, v198
	v_bfe_u32 v199, v32, 5, 1
	s_addc_u32 s55, s27, s55
	v_lshlrev_b64 v[0:1], 8, v[184:185]
	v_lshl_add_u64 v[0:1], s[54:55], 0, v[0:1]
	v_lshlrev_b32_e32 v184, 4, v199
	v_lshl_add_u64 v[28:29], v[0:1], 0, v[184:185]
	global_load_dwordx4 v[160:163], v[28:29], off
	global_load_dwordx4 v[164:167], v[28:29], off offset:32
	global_load_dwordx4 v[168:171], v[28:29], off offset:64
	global_load_dwordx4 v[172:175], v[28:29], off offset:96
	global_load_dwordx4 v[176:179], v[28:29], off offset:128
	global_load_dwordx4 v[180:183], v[28:29], off offset:160
	global_load_dwordx4 v[240:243], v[28:29], off offset:192
	s_nop 0
	global_load_dwordx4 v[244:247], v[28:29], off offset:224
	v_add_u32_e32 v40, s64, v32
	v_and_b32_e32 v195, 63, v32
	v_lshlrev_b32_e32 v41, 3, v32
	s_mov_b32 s5, s45
	v_lshlrev_b32_e32 v34, 1, v32
	v_ashrrev_i32_e32 v42, 4, v40
	v_and_b32_e32 v43, 0x78, v41
	v_lshlrev_b32_e32 v196, 4, v195
	v_lshlrev_b32_e32 v36, 4, v32
	v_lshlrev_b32_e32 v197, 3, v195
	v_and_b32_e32 v37, 32, v34
	v_and_b32_e32 v34, 0xc0, v196
	v_lshl_or_b32 v32, v42, 7, v43
	s_lshl_b64 s[4:5], s[4:5], 1
	v_mov_b32_e32 v35, v185
	v_lshlrev_b32_e32 v44, 8, v198
	v_and_or_b32 v39, v197, 24, v34
	v_add_u32_e32 v34, 0x1000, v32
	s_add_u32 s4, s26, s4
	v_mov_b32_e32 v33, v185
	v_and_b32_e32 v45, 0x70, v36
	v_and_b32_e32 v38, 0x100, v197
	v_add_u32_e32 v46, s9, v44
	v_bitop3_b32 v36, v184, v36, s71 bitop3:0x78
	v_lshlrev_b64 v[188:189], 1, v[34:35]
	s_addc_u32 s5, s27, s5
	v_lshlrev_b64 v[186:187], 1, v[32:33]
	v_or3_b32 v56, v39, v37, v38
	v_mov_b32_e32 v239, v56
	v_add_u32_e32 v57, v46, v36
	s_add_u32 s54, s4, 0x4080000
	s_addc_u32 s55, s5, 0
	s_add_i32 s99, s100, 0x8000
	s_mov_b32 m0, s99
	s_nop 0
	global_load_lds_dwordx4 v232, s[54:55]
	s_add_i32 m0, s99, 0x2000
	s_nop 0
	global_load_lds_dwordx4 v233, s[54:55]
	s_mov_b32 m0, s100
	s_nop 0
	global_load_lds_dwordx4 v234, s[48:49]
	s_add_i32 m0, s100, 0x2000
	s_nop 0
	global_load_lds_dwordx4 v235, s[48:49]
	s_add_i32 m0, s100, 0x4000
	s_nop 0
	global_load_lds_dwordx4 v234, s[6:7]
	s_add_i32 m0, s100, 0x6000
	s_nop 0
	global_load_lds_dwordx4 v235, s[6:7]
	s_movk_i32 s14, 0x60
	v_bitop3_b32 v48, v184, v45, 32 bitop3:0x36
	v_bitop3_b32 v50, v184, v45, 64 bitop3:0x36
	v_bitop3_b32 v52, v184, v45, s14 bitop3:0x36
	v_or_b32_e32 v53, 0x80, v184
	v_or_b32_e32 v54, 0xa0, v184
	v_or_b32_e32 v55, 0xc0, v184
	v_add_u32_e32 v48, v46, v48
	v_add_u32_e32 v50, v46, v50
	v_add_u32_e32 v52, v46, v52
	v_xad_u32 v53, v53, v45, v46
	v_xad_u32 v54, v54, v45, v46
	v_xad_u32 v55, v55, v45, v46
	s_cmp_lg_u32 0, -1
	s_cselect_b32 s4, 0, 0
	v_add_u32_e32 v200, s4, v56
	s_add_i32 s4, 0, 0x8000
	s_cmp_lg_u32 s4, -1
	v_or_b32_e32 v47, 32, v184
	s_cselect_b32 s4, s4, 0
	v_or_b32_e32 v49, 64, v184
	v_or_b32_e32 v51, 0x60, v184
	v_mov_b32_e32 v64, v185
	v_mov_b32_e32 v65, v185
	v_mov_b32_e32 v78, v185
	v_mov_b32_e32 v79, v185
	v_mov_b32_e32 v66, v185
	v_mov_b32_e32 v67, v185
	v_mov_b32_e32 v68, v185
	v_mov_b32_e32 v69, v185
	v_mov_b32_e32 v70, v185
	v_mov_b32_e32 v71, v185
	v_lshrrev_b32_e32 v4, 1, v42
	v_and_b32_e32 v5, 3, v42
	v_and_or_b32 v4, v4, 4, v5
	v_add_u32_e32 v5, 32, v42
	v_lshlrev_b32_e32 v2, 1, v42
	v_and_b32_e32 v3, 0xfffff0, v42
	v_lshlrev_b32_e32 v6, 1, v5
	v_and_b32_e32 v5, 0xfffff0, v5
	v_or_b32_e32 v0, 0xe0, v184
	v_and_or_b32 v2, v2, 8, v3
	v_and_or_b32 v5, v6, 8, v5
	v_xad_u32 v0, v0, v45, v46
	v_lshrrev_b32_e32 v2, 1, v2
	v_bfe_u32 v3, v41, 5, 2
	v_lshrrev_b32_e32 v5, 1, v5
	v_lshlrev_b32_e32 v0, 1, v43
	v_or_b32_e32 v2, v2, v3
	v_or_b32_e32 v3, v5, v3
	v_bitop3_b32 v1, v0, v40, s71 bitop3:0x78
	v_lshlrev_b32_e32 v2, 9, v2
	v_lshlrev_b32_e32 v4, 6, v4
	v_and_b32_e32 v0, 48, v0
	v_lshlrev_b32_e32 v3, 9, v3
	v_or3_b32 v2, v2, v4, v0
	v_or3_b32 v0, v3, v4, v0
	v_bitop3_b32 v4, v184, v44, v45 bitop3:0xde
	v_add_u32_e32 v201, s4, v4
	v_add_u32_e32 v202, s61, v4
	v_bitop3_b32 v4, v47, v44, v45 bitop3:0xde
	v_add_u32_e32 v203, s4, v4
	v_add_u32_e32 v204, s61, v4
	v_bitop3_b32 v4, v49, v44, v45 bitop3:0xde
	v_lshl_add_u32 v3, v42, 8, 0
	v_add_u32_e32 v206, s4, v4
	v_add_u32_e32 v207, s61, v4
	v_bitop3_b32 v4, v51, v44, v45 bitop3:0xde
	v_add_u32_e32 v208, s4, v4
	v_add_u32_e32 v209, s61, v4
	v_mov_b32_e32 v72, v185
	v_mov_b32_e32 v73, v185
	v_mov_b32_e32 v74, v185
	v_mov_b32_e32 v75, v185
	v_mov_b32_e32 v76, v185
	v_mov_b32_e32 v77, v185
	v_add_u32_e32 v211, v3, v1
	v_mov_b64_e32 v[126:127], v[78:79]
	v_mov_b64_e32 v[110:111], v[78:79]
	v_mov_b64_e32 v[94:95], v[78:79]
	v_mov_b64_e32 v[48:49], v[64:65]
	v_mov_b64_e32 v[32:33], v[64:65]
	v_mov_b64_e32 v[16:17], v[64:65]
	v_mov_b64_e32 v[0:1], v[64:65]
	s_mov_b32 s44, 64
	v_cmp_gt_u32_e64 s[4:5], 32, v195
	v_lshl_add_u32 v205, v198, 2, s63
	v_mov_b32_e32 v214, 0
	v_mov_b32_e32 v210, 0xf149f2ca
	v_mov_b64_e32 v[124:125], v[76:77]
	v_mov_b64_e32 v[122:123], v[74:75]
	v_mov_b64_e32 v[120:121], v[72:73]
	v_mov_b64_e32 v[118:119], v[70:71]
	v_mov_b64_e32 v[116:117], v[68:69]
	v_mov_b64_e32 v[114:115], v[66:67]
	v_mov_b64_e32 v[112:113], v[64:65]
	v_mov_b64_e32 v[108:109], v[76:77]
	v_mov_b64_e32 v[106:107], v[74:75]
	v_mov_b64_e32 v[104:105], v[72:73]
	v_mov_b64_e32 v[102:103], v[70:71]
	v_mov_b64_e32 v[100:101], v[68:69]
	v_mov_b64_e32 v[98:99], v[66:67]
	v_mov_b64_e32 v[96:97], v[64:65]
	v_mov_b64_e32 v[92:93], v[76:77]
	v_mov_b64_e32 v[90:91], v[74:75]
	v_mov_b64_e32 v[88:89], v[72:73]
	v_mov_b64_e32 v[86:87], v[70:71]
	v_mov_b64_e32 v[84:85], v[68:69]
	v_mov_b64_e32 v[82:83], v[66:67]
	v_mov_b64_e32 v[80:81], v[64:65]
	v_mov_b64_e32 v[50:51], v[66:67]
	v_mov_b64_e32 v[52:53], v[68:69]
	v_mov_b64_e32 v[54:55], v[70:71]
	v_mov_b64_e32 v[56:57], v[72:73]
	v_mov_b64_e32 v[58:59], v[74:75]
	v_mov_b64_e32 v[60:61], v[76:77]
	v_mov_b64_e32 v[62:63], v[78:79]
	v_mov_b64_e32 v[34:35], v[66:67]
	v_mov_b64_e32 v[36:37], v[68:69]
	v_mov_b64_e32 v[38:39], v[70:71]
	v_mov_b64_e32 v[40:41], v[72:73]
	v_mov_b64_e32 v[42:43], v[74:75]
	v_mov_b64_e32 v[44:45], v[76:77]
	v_mov_b64_e32 v[46:47], v[78:79]
	v_mov_b64_e32 v[18:19], v[66:67]
	v_mov_b64_e32 v[20:21], v[68:69]
	v_mov_b64_e32 v[22:23], v[70:71]
	v_mov_b64_e32 v[24:25], v[72:73]
	v_mov_b64_e32 v[26:27], v[74:75]
	v_mov_b64_e32 v[28:29], v[76:77]
	v_mov_b64_e32 v[30:31], v[78:79]
	v_mov_b64_e32 v[2:3], v[66:67]
	v_mov_b64_e32 v[4:5], v[68:69]
	v_mov_b64_e32 v[6:7], v[70:71]
	v_mov_b64_e32 v[8:9], v[72:73]
	v_mov_b64_e32 v[10:11], v[74:75]
	v_mov_b64_e32 v[12:13], v[76:77]
	v_mov_b64_e32 v[14:15], v[78:79]
	s_mov_b32 s56, 0
.LBB0_397:
	s_waitcnt vmcnt(0)
	s_add_i32 s96, s56, 1
	s_cmp_ge_i32 s96, s93
	s_waitcnt lgkmcnt(0)
	s_barrier
	s_cbranch_scc1 .LBB0_399
	s_lshl_b64 vcc, s[44:45], 8
	s_add_u32 s24, s54, vcc_lo
	s_addc_u32 s25, s55, vcc_hi
	s_add_u32 s14, s48, vcc_lo
	s_addc_u32 s15, s49, vcc_hi
	s_and_b32 s97, s96, 1
	s_mul_i32 s97, s97, 0x14000
	s_add_i32 s97, s97, 0x8000
	s_mov_b32 s98, s96
	s_mul_i32 s99, s98, 171
	s_lshr_b32 s99, s99, 9
	s_mul_i32 s99, s99, 3
	s_sub_i32 s98, s98, s99
	s_mul_i32 s99, s98, 0xc000
	s_cmp_eq_u32 s98, 2
	s_cselect_b32 s98, 0x4000, 0
	s_sub_i32 s98, s99, s98
	s_add_i32 s98, s98, s100
	s_add_i32 s99, s97, s100
	s_mov_b32 m0, s99
	s_nop 0
	global_load_lds_dwordx4 v232, s[24:25]
	s_add_i32 m0, s99, 0x2000
	s_nop 0
	global_load_lds_dwordx4 v233, s[24:25]
	s_mov_b32 m0, s98
	s_nop 0
	global_load_lds_dwordx4 v234, s[14:15]
	s_add_i32 m0, s98, 0x2000
	s_nop 0
	global_load_lds_dwordx4 v235, s[14:15]
	s_add_u32 s24, s6, vcc_lo
	s_addc_u32 s25, s7, vcc_hi
	s_add_i32 m0, s98, 0x4000
	s_nop 0
	global_load_lds_dwordx4 v234, s[24:25]
	s_add_i32 m0, s98, 0x6000
	s_nop 0
	global_load_lds_dwordx4 v235, s[24:25]
.LBB0_399:
	s_cmp_eq_u32 s101, 0
	s_cbranch_scc1 .Ldiff_qk_entry
	s_cmp_lt_u32 s96, 2
	s_cbranch_scc1 .Ldiff_qk_entry
	s_add_i32 s98, s96, -2
	s_cmp_ge_i32 s98, s94
	s_cbranch_scc1 .Ldiff_qk_entry
	s_mul_i32 s99, s98, 171
	s_lshr_b32 s99, s99, 9
	s_mul_i32 s99, s99, 3
	s_sub_i32 s98, s98, s99
	s_mul_i32 s99, s98, 0xc000
	s_cmp_eq_u32 s98, 2
	s_cselect_b32 s98, 0x4000, 0
	s_sub_i32 s98, s99, s98
	v_add_u32_e32 v200, s98, v239
	s_mov_b32 s97, 1
	s_branch .Ldiff_pv
.Ldiff_qk_entry:
	s_add_i32 s98, s96, -1
	s_cmp_ge_i32 s98, s94
	s_cbranch_scc1 .LBB0_405
	ds_read_b128 v[128:131], v201 offset:0
	ds_read_b128 v[148:151], v201 offset:0x2000
	ds_read_b128 v[216:219], v203 offset:0
	ds_read_b128 v[220:223], v203 offset:0x2000
	s_waitcnt lgkmcnt(2)
	s_nop 0
	v_mfma_f32_32x32x16_bf16 v[128:143], v[128:131], v[160:163], 0
	v_mfma_f32_32x32x16_bf16 v[144:159], v[148:151], v[160:163], 0
	ds_read_b128 v[224:227], v206 offset:0
	ds_read_b128 v[228:231], v206 offset:0x2000
	s_waitcnt lgkmcnt(2)
	v_mfma_f32_32x32x16_bf16 v[128:143], v[216:219], v[164:167], v[128:143]
	v_mfma_f32_32x32x16_bf16 v[144:159], v[220:223], v[164:167], v[144:159]
	ds_read_b128 v[216:219], v208 offset:0
	ds_read_b128 v[220:223], v208 offset:0x2000
	s_waitcnt lgkmcnt(2)
	v_mfma_f32_32x32x16_bf16 v[128:143], v[224:227], v[168:171], v[128:143]
	v_mfma_f32_32x32x16_bf16 v[144:159], v[228:231], v[168:171], v[144:159]
	ds_read_b128 v[224:227], v201 offset:0x80
	ds_read_b128 v[228:231], v201 offset:0x2080
	s_waitcnt lgkmcnt(2)
	v_mfma_f32_32x32x16_bf16 v[128:143], v[216:219], v[172:175], v[128:143]
	v_mfma_f32_32x32x16_bf16 v[144:159], v[220:223], v[172:175], v[144:159]
	ds_read_b128 v[216:219], v203 offset:0x80
	ds_read_b128 v[220:223], v203 offset:0x2080
	s_waitcnt lgkmcnt(2)
	v_mfma_f32_32x32x16_bf16 v[128:143], v[224:227], v[176:179], v[128:143]
	v_mfma_f32_32x32x16_bf16 v[144:159], v[228:231], v[176:179], v[144:159]
	ds_read_b128 v[224:227], v206 offset:0x80
	ds_read_b128 v[228:231], v206 offset:0x2080
	s_waitcnt lgkmcnt(2)
	v_mfma_f32_32x32x16_bf16 v[128:143], v[216:219], v[180:183], v[128:143]
	v_mfma_f32_32x32x16_bf16 v[144:159], v[220:223], v[180:183], v[144:159]
	ds_read_b128 v[216:219], v208 offset:0x80
	ds_read_b128 v[220:223], v208 offset:0x2080
	s_waitcnt lgkmcnt(2)
	v_mfma_f32_32x32x16_bf16 v[128:143], v[224:227], v[240:243], v[128:143]
	v_mfma_f32_32x32x16_bf16 v[144:159], v[228:231], v[240:243], v[144:159]
	s_waitcnt lgkmcnt(0)
	v_mfma_f32_32x32x16_bf16 v[128:143], v[216:219], v[244:247], v[128:143]
	s_cmp_eq_u32 s56, 0
	s_cselect_b64 vcc, -1, 0
	s_mov_b32 s14, 0x41000000
	v_mfma_f32_32x32x16_bf16 v[144:159], v[220:223], v[244:247], v[144:159]
	s_cbranch_scc1 .Ldiff_pad
	s_nop 7
	v_max_f32_e32 v215, v128, v129
	v_max3_f32 v215, v215, v130, v131
	v_max3_f32 v215, v215, v132, v133
	v_max3_f32 v215, v215, v134, v135
	v_max3_f32 v215, v215, v136, v137
	v_max3_f32 v215, v215, v138, v139
	v_max3_f32 v215, v215, v140, v141
	v_max3_f32 v215, v215, v142, v143
	v_max3_f32 v215, v215, v144, v145
	v_max3_f32 v215, v215, v146, v147
	v_max3_f32 v215, v215, v148, v149
	v_max3_f32 v215, v215, v150, v151
	v_max3_f32 v215, v215, v152, v153
	v_max3_f32 v215, v215, v154, v155
	v_max3_f32 v215, v215, v156, v157
	v_max3_f32 v215, v215, v158, v159
	s_branch .Ldiff_padjoin

.Ldiff_sm_join:
	s_cmp_lg_u32 s101, 0
	s_cbranch_scc1 .LBB0_405
	s_add_i32 s98, s96, -1
	s_mul_i32 s99, s98, 171
	s_lshr_b32 s99, s99, 9
	s_mul_i32 s99, s99, 3
	s_sub_i32 s98, s98, s99
	s_mul_i32 s99, s98, 0xc000
	s_cmp_eq_u32 s98, 2
	s_cselect_b32 s98, 0x4000, 0
	s_sub_i32 s98, s99, s98
	v_add_u32_e32 v200, s98, v239
	s_mov_b32 s97, 0
.Ldiff_pv:
	ds_read_b64_tr_b16 v[144:145], v200 offset:0
	ds_read_b64_tr_b16 v[146:147], v200 offset:0x800
	ds_read_b64_tr_b16 v[148:149], v200 offset:0x1000
	ds_read_b64_tr_b16 v[150:151], v200 offset:0x1800
	ds_read_b64_tr_b16 v[152:153], v200 offset:0x2000
	ds_read_b64_tr_b16 v[154:155], v200 offset:0x2800
	ds_read_b64_tr_b16 v[156:157], v200 offset:0x3000
	ds_read_b64_tr_b16 v[158:159], v200 offset:0x3800
	s_waitcnt lgkmcnt(0)
	ds_read_b64_tr_b16 v[214:215], v200 offset:0x200
	ds_read_b64_tr_b16 v[216:217], v200 offset:0xa00
	ds_read_b64_tr_b16 v[218:219], v200 offset:0x1200
	ds_read_b64_tr_b16 v[220:221], v200 offset:0x1a00
	ds_read_b64_tr_b16 v[222:223], v200 offset:0x2200
	ds_read_b64_tr_b16 v[224:225], v200 offset:0x2a00
	ds_read_b64_tr_b16 v[226:227], v200 offset:0x3200
	ds_read_b64_tr_b16 v[228:229], v200 offset:0x3a00
	s_nop 0
	v_mfma_f32_32x32x16_bf16 v[64:79], v[128:131], v[144:147], v[64:79]
	v_mfma_f32_32x32x16_bf16 v[64:79], v[132:135], v[148:151], v[64:79]
	v_mfma_f32_32x32x16_bf16 v[64:79], v[136:139], v[152:155], v[64:79]
	v_mfma_f32_32x32x16_bf16 v[64:79], v[140:143], v[156:159], v[64:79]
	s_waitcnt lgkmcnt(0)
	ds_read_b64_tr_b16 v[144:145], v200 offset:0x400
	ds_read_b64_tr_b16 v[146:147], v200 offset:0xc00
	ds_read_b64_tr_b16 v[148:149], v200 offset:0x1400
	ds_read_b64_tr_b16 v[150:151], v200 offset:0x1c00
	ds_read_b64_tr_b16 v[152:153], v200 offset:0x2400
	ds_read_b64_tr_b16 v[154:155], v200 offset:0x2c00
	ds_read_b64_tr_b16 v[156:157], v200 offset:0x3400
	ds_read_b64_tr_b16 v[158:159], v200 offset:0x3c00
	v_mfma_f32_32x32x16_bf16 v[112:127], v[128:131], v[214:217], v[112:127]
	v_mfma_f32_32x32x16_bf16 v[112:127], v[132:135], v[218:221], v[112:127]
	v_mfma_f32_32x32x16_bf16 v[112:127], v[136:139], v[222:225], v[112:127]
	v_mfma_f32_32x32x16_bf16 v[112:127], v[140:143], v[226:229], v[112:127]
	s_waitcnt lgkmcnt(0)
	ds_read_b64_tr_b16 v[214:215], v200 offset:0x600
	ds_read_b64_tr_b16 v[216:217], v200 offset:0xe00
	ds_read_b64_tr_b16 v[218:219], v200 offset:0x1600
	ds_read_b64_tr_b16 v[220:221], v200 offset:0x1e00
	ds_read_b64_tr_b16 v[222:223], v200 offset:0x2600
	ds_read_b64_tr_b16 v[224:225], v200 offset:0x2e00
	ds_read_b64_tr_b16 v[226:227], v200 offset:0x3600
	ds_read_b64_tr_b16 v[228:229], v200 offset:0x3e00
	v_mfma_f32_32x32x16_bf16 v[96:111], v[128:131], v[144:147], v[96:111]
	v_mfma_f32_32x32x16_bf16 v[96:111], v[132:135], v[148:151], v[96:111]
	v_mfma_f32_32x32x16_bf16 v[96:111], v[136:139], v[152:155], v[96:111]
	v_mfma_f32_32x32x16_bf16 v[96:111], v[140:143], v[156:159], v[96:111]
	s_waitcnt lgkmcnt(0)
	ds_read_b64_tr_b16 v[144:145], v200 offset:0x4000
	ds_read_b64_tr_b16 v[146:147], v200 offset:0x4800
	ds_read_b64_tr_b16 v[148:149], v200 offset:0x5000
	ds_read_b64_tr_b16 v[150:151], v200 offset:0x5800
	ds_read_b64_tr_b16 v[152:153], v200 offset:0x6000
	ds_read_b64_tr_b16 v[154:155], v200 offset:0x6800
	ds_read_b64_tr_b16 v[156:157], v200 offset:0x7000
	ds_read_b64_tr_b16 v[158:159], v200 offset:0x7800
	v_mfma_f32_32x32x16_bf16 v[80:95], v[128:131], v[214:217], v[80:95]
	v_mfma_f32_32x32x16_bf16 v[80:95], v[132:135], v[218:221], v[80:95]
	v_mfma_f32_32x32x16_bf16 v[80:95], v[136:139], v[222:225], v[80:95]
	v_mfma_f32_32x32x16_bf16 v[80:95], v[140:143], v[226:229], v[80:95]
	s_waitcnt lgkmcnt(0)
	ds_read_b64_tr_b16 v[214:215], v200 offset:0x4200
	ds_read_b64_tr_b16 v[216:217], v200 offset:0x4a00
	ds_read_b64_tr_b16 v[218:219], v200 offset:0x5200
	ds_read_b64_tr_b16 v[220:221], v200 offset:0x5a00
	ds_read_b64_tr_b16 v[222:223], v200 offset:0x6200
	ds_read_b64_tr_b16 v[224:225], v200 offset:0x6a00
	ds_read_b64_tr_b16 v[226:227], v200 offset:0x7200
	ds_read_b64_tr_b16 v[228:229], v200 offset:0x7a00
	v_mfma_f32_32x32x16_bf16 v[48:63], v[128:131], v[144:147], v[48:63]
	v_mfma_f32_32x32x16_bf16 v[48:63], v[132:135], v[148:151], v[48:63]
	v_mfma_f32_32x32x16_bf16 v[48:63], v[136:139], v[152:155], v[48:63]
	v_mfma_f32_32x32x16_bf16 v[48:63], v[140:143], v[156:159], v[48:63]
	s_waitcnt lgkmcnt(0)
	ds_read_b64_tr_b16 v[144:145], v200 offset:0x4400
	ds_read_b64_tr_b16 v[146:147], v200 offset:0x4c00
	ds_read_b64_tr_b16 v[148:149], v200 offset:0x5400
	ds_read_b64_tr_b16 v[150:151], v200 offset:0x5c00
	ds_read_b64_tr_b16 v[152:153], v200 offset:0x6400
	ds_read_b64_tr_b16 v[154:155], v200 offset:0x6c00
	ds_read_b64_tr_b16 v[156:157], v200 offset:0x7400
	ds_read_b64_tr_b16 v[158:159], v200 offset:0x7c00
	v_mfma_f32_32x32x16_bf16 v[32:47], v[128:131], v[214:217], v[32:47]
	v_mfma_f32_32x32x16_bf16 v[32:47], v[132:135], v[218:221], v[32:47]
	v_mfma_f32_32x32x16_bf16 v[32:47], v[136:139], v[222:225], v[32:47]
	v_mfma_f32_32x32x16_bf16 v[32:47], v[140:143], v[226:229], v[32:47]
	s_waitcnt lgkmcnt(0)
	ds_read_b64_tr_b16 v[214:215], v200 offset:0x4600
	ds_read_b64_tr_b16 v[216:217], v200 offset:0x4e00
	ds_read_b64_tr_b16 v[218:219], v200 offset:0x5600
	ds_read_b64_tr_b16 v[220:221], v200 offset:0x5e00
	ds_read_b64_tr_b16 v[222:223], v200 offset:0x6600
	ds_read_b64_tr_b16 v[224:225], v200 offset:0x6e00
	ds_read_b64_tr_b16 v[226:227], v200 offset:0x7600
	ds_read_b64_tr_b16 v[228:229], v200 offset:0x7e00
	v_mfma_f32_32x32x16_bf16 v[16:31], v[128:131], v[144:147], v[16:31]
	v_mfma_f32_32x32x16_bf16 v[16:31], v[132:135], v[148:151], v[16:31]
	v_mfma_f32_32x32x16_bf16 v[16:31], v[136:139], v[152:155], v[16:31]
	v_mfma_f32_32x32x16_bf16 v[16:31], v[140:143], v[156:159], v[16:31]
	s_waitcnt lgkmcnt(0)
	v_mfma_f32_32x32x16_bf16 v[0:15], v[128:131], v[214:217], v[0:15]
	v_mov_b32_e32 v214, v230
	v_mfma_f32_32x32x16_bf16 v[0:15], v[132:135], v[218:221], v[0:15]
	v_mfma_f32_32x32x16_bf16 v[0:15], v[136:139], v[222:225], v[0:15]
	v_mfma_f32_32x32x16_bf16 v[0:15], v[140:143], v[226:229], v[0:15]
	s_cmp_eq_u32 s97, 1
	s_cbranch_scc1 .Ldiff_qk_entry
	s_cmp_eq_u32 s97, 2
	s_cbranch_scc1 .Ldiff_drain_done
.LBB0_405:
	v_xor_b32_e32 v201, 0x14000, v201
	v_xor_b32_e32 v203, 0x14000, v203
	v_xor_b32_e32 v206, 0x14000, v206
	v_xor_b32_e32 v208, 0x14000, v208
	s_add_i32 s44, s44, 64
	s_cmp_eq_u32 s95, s96
	s_cbranch_scc1 .LBB0_407
	s_mov_b32 s56, s96
	s_branch .LBB0_397

.LBB0_407:
	s_cmp_eq_u32 s101, 0
	s_cbranch_scc1 .Ldiff_drain_done
	s_add_i32 s98, s93, -1
	s_cmp_ge_i32 s98, s94
	s_cbranch_scc1 .Ldiff_drain_done
	s_mul_i32 s99, s98, 171
	s_lshr_b32 s99, s99, 9
	s_mul_i32 s99, s99, 3
	s_sub_i32 s98, s98, s99
	s_mul_i32 s99, s98, 0xc000
	s_cmp_eq_u32 s98, 2
	s_cselect_b32 s98, 0x4000, 0
	s_sub_i32 s98, s99, s98
	v_add_u32_e32 v200, s98, v239
	s_mov_b32 s97, 2
	s_branch .Ldiff_pv
